# last-unit write-through stores in all six GEMM epilogue variants (incl. all of layer-0 G2) + early barrier acquire
# speedup vs baseline: 1.0045x; 1.0045x over previous
.LBB0_911:
	s_lshl_b32 s15, s92, 8
	s_add_i32 s5, s15, 0xffffc000
	s_lshr_b32 s5, s5, 12
	s_ashr_i32 s4, s92, 5
	s_add_i32 s5, s5, 2
	s_cmp_lt_i32 s92, 64
	v_add_u32_e32 v214, s15, v222
	v_readlane_b32 s56, v252, 3
	s_cselect_b32 s4, s4, s5
	v_add_u32_e32 v88, 0xffffc000, v214
	v_ashrrev_i32_e32 v215, 31, v214
	v_cmp_gt_i32_e32 vcc, s21, v214
	v_readlane_b32 s57, v252, 4
	v_readlane_b32 s58, v252, 5
	v_readlane_b32 s59, v252, 6
	v_lshl_or_b32 v212, s18, 8, v224
	s_ashr_i32 s5, s4, 31
	v_cndmask_b32_e32 v89, 0, v215, vcc
	v_cndmask_b32_e32 v88, v88, v214, vcc
	v_mov_b32_e32 v170, s59
	v_mov_b32_e32 v171, s57
	v_mov_b32_e32 v172, s58
	v_mov_b32_e32 v173, s56
	s_lshl_b64 s[4:5], s[4:5], 14
	v_ashrrev_i32_e32 v213, 31, v212
	v_cndmask_b32_e32 v91, v170, v171, vcc
	v_cndmask_b32_e32 v90, v172, v173, vcc
	v_lshlrev_b64 v[88:89], 12, v[88:89]
	s_add_u32 s44, s79, s4
	v_lshlrev_b64 v[164:165], 2, v[212:213]
	v_lshl_add_u64 v[88:89], v[90:91], 0, v[88:89]
	s_addc_u32 s45, s88, s5
	v_lshl_add_u64 v[166:167], v[88:89], 0, v[164:165]
	v_lshl_add_u64 v[86:87], s[44:45], 0, v[164:165]
	global_load_dwordx4 v[238:241], v[166:167], off
	global_load_dwordx4 v[124:127], v[86:87], off
	global_load_dwordx4 v[116:119], v[86:87], off offset:16
	global_load_dwordx4 v[242:245], v[166:167], off offset:16
	s_add_u32 s4, s89, s4
	s_addc_u32 s5, s90, s5
	v_lshl_add_u64 v[90:91], s[4:5], 0, v[164:165]
	global_load_dwordx4 v[112:115], v[90:91], off
	global_load_dwordx4 v[108:111], v[90:91], off offset:16
	global_load_dwordx4 v[100:103], v[86:87], off offset:528
	global_load_dwordx4 v[104:107], v[86:87], off offset:512
	s_nop 0
	global_load_dwordx4 v[86:89], v[90:91], off offset:528
	s_nop 0
	global_load_dwordx4 v[90:93], v[90:91], off offset:512
	s_nop 0
	global_load_dwordx4 v[246:249], v[166:167], off offset:528
	global_load_dwordx4 v[200:203], v[166:167], off offset:512
	v_or_b32_e32 v220, 16, v214
	v_ashrrev_i32_e32 v221, 31, v220
	v_add_u32_e32 v166, 0xffffc010, v214
	v_cmp_gt_i32_e32 vcc, s21, v220
	v_or_b32_e32 v216, 32, v214
	v_ashrrev_i32_e32 v217, 31, v216
	v_cndmask_b32_e32 v167, 0, v221, vcc
	v_cndmask_b32_e32 v166, v166, v220, vcc
	v_cndmask_b32_e32 v169, v170, v171, vcc
	v_cndmask_b32_e32 v168, v172, v173, vcc
	v_lshlrev_b64 v[166:167], 12, v[166:167]
	v_lshl_add_u64 v[166:167], v[168:169], 0, v[166:167]
	v_lshl_add_u64 v[166:167], v[166:167], 0, v[164:165]
	global_load_dwordx4 v[188:191], v[166:167], off offset:16
	global_load_dwordx4 v[192:195], v[166:167], off
	global_load_dwordx4 v[180:183], v[166:167], off offset:528
	global_load_dwordx4 v[184:187], v[166:167], off offset:512
	v_add_u32_e32 v166, 0xffffc020, v214
	v_cmp_gt_i32_e32 vcc, s21, v216
	v_and_b32_e32 v211, 64, v229
	v_xor_b32_e32 v210, 16, v229
	v_cndmask_b32_e32 v167, 0, v217, vcc
	v_cndmask_b32_e32 v166, v166, v216, vcc
	v_cndmask_b32_e32 v169, v170, v171, vcc
	v_cndmask_b32_e32 v168, v172, v173, vcc
	v_lshlrev_b64 v[166:167], 12, v[166:167]
	v_lshl_add_u64 v[166:167], v[168:169], 0, v[166:167]
	v_lshl_add_u64 v[168:169], v[166:167], 0, v[164:165]
	global_load_dwordx4 v[172:175], v[168:169], off offset:16
	global_load_dwordx4 v[176:179], v[168:169], off
	global_load_dwordx4 v[164:167], v[168:169], off offset:528
	s_nop 0
	global_load_dwordx4 v[168:171], v[168:169], off offset:512
	v_add_u32_e32 v211, 64, v211
	v_xor_b32_e32 v218, 32, v229
	v_cmp_lt_i32_e32 vcc, v210, v211
	s_lshl_b32 s56, s18, 2
	v_readlane_b32 s68, v252, 15
	v_cndmask_b32_e32 v210, v229, v210, vcc
	v_cmp_lt_i32_e32 vcc, v218, v211
	v_lshlrev_b32_e32 v227, 2, v210
	v_readlane_b32 s69, v252, 16
	v_cndmask_b32_e32 v211, v229, v218, vcc
	v_lshlrev_b32_e32 v226, 2, v211
	v_lshlrev_b64 v[210:211], 1, v[212:213]
	s_ashr_i32 s57, s56, 31
	v_readlane_b32 s60, v252, 7
	v_readlane_b32 s61, v252, 8
	v_readlane_b32 s62, v252, 9
	v_readlane_b32 s63, v252, 10
	v_readlane_b32 s64, v252, 11
	v_readlane_b32 s65, v252, 12
	v_readlane_b32 s66, v252, 13
	v_readlane_b32 s67, v252, 14
	v_readlane_b32 s70, v252, 17
	v_readlane_b32 s71, v252, 18
	s_waitcnt vmcnt(0)
	v_pk_fma_f32 v[160:161], v[160:161], v[124:125], v[238:239]
	v_pk_fma_f32 v[162:163], v[162:163], v[126:127], v[240:241]
	v_pk_fma_f32 v[218:219], v[158:159], v[118:119], v[244:245]
	v_pk_fma_f32 v[238:239], v[156:157], v[116:117], v[242:243]
	v_pk_mul_f32 v[156:157], v[218:219], v[218:219]
	v_pk_mul_f32 v[158:159], v[238:239], v[238:239]
	v_pk_fma_f32 v[156:157], v[162:163], v[162:163], v[156:157]
	v_pk_fma_f32 v[158:159], v[160:161], v[160:161], v[158:159]
	v_lshlrev_b64 v[240:241], 11, v[214:215]
	v_add_f32_e32 v158, v158, v159
	v_add_f32_e32 v156, v156, v157
	v_lshl_add_u64 v[242:243], s[82:83], 0, v[240:241]
	v_add_f32_e32 v244, v158, v156
	v_cvt_pk_bf16_f32 v156, v160, v161
	v_cvt_pk_bf16_f32 v157, v162, v163
	v_cvt_pk_bf16_f32 v158, v238, v239
	v_cvt_pk_bf16_f32 v159, v218, v219
	v_lshl_add_u64 v[242:243], v[242:243], 0, v[210:211]
	s_andn2_b64 vcc, exec, s[38:39]
	s_cbranch_vccnz .Lmy_wt_g2b_0
	global_store_dwordx4 v[242:243], v[156:159], off
.Lmy_wt_g2b_0r:
	v_pk_fma_f32 v[154:155], v[154:155], v[106:107], v[202:203]
	v_pk_fma_f32 v[152:153], v[152:153], v[104:105], v[200:201]
	v_pk_mul_f32 v[158:159], v[114:115], v[162:163]
	v_pk_mul_f32 v[156:157], v[112:113], v[160:161]
	v_pk_mul_f32 v[160:161], v[110:111], v[218:219]
	v_pk_mul_f32 v[162:163], v[108:109], v[238:239]
	v_cvt_pk_bf16_f32 v156, v156, v157
	v_cvt_pk_bf16_f32 v157, v158, v159
	v_cvt_pk_bf16_f32 v159, v160, v161
	v_lshl_add_u64 v[160:161], s[22:23], 0, v[240:241]
	v_cvt_pk_bf16_f32 v158, v162, v163
	v_lshl_add_u64 v[160:161], v[160:161], 0, v[210:211]
	s_andn2_b64 vcc, exec, s[38:39]
	s_cbranch_vccnz .Lmy_wt_g2b_1
	global_store_dwordx4 v[160:161], v[156:159], off
.Lmy_wt_g2b_1r:
	s_nop 1
	v_pk_fma_f32 v[156:157], v[150:151], v[102:103], v[248:249]
	v_pk_fma_f32 v[158:159], v[148:149], v[100:101], v[246:247]
	v_pk_mul_f32 v[148:149], v[156:157], v[156:157]
	v_pk_mul_f32 v[150:151], v[158:159], v[158:159]
	v_pk_fma_f32 v[148:149], v[154:155], v[154:155], v[148:149]
	v_pk_fma_f32 v[150:151], v[152:153], v[152:153], v[150:151]
	v_add_f32_e32 v148, v148, v149
	v_add_f32_e32 v150, v150, v151
	v_add_f32_e32 v148, v150, v148
	v_add_f32_e32 v162, v244, v148
	v_cvt_pk_bf16_f32 v148, v152, v153
	v_cvt_pk_bf16_f32 v149, v154, v155
	v_cvt_pk_bf16_f32 v150, v158, v159
	v_cvt_pk_bf16_f32 v151, v156, v157
	s_andn2_b64 vcc, exec, s[38:39]
	s_cbranch_vccnz .Lmy_wt_g2b_2
	global_store_dwordx4 v[242:243], v[148:151], off offset:256
.Lmy_wt_g2b_2r:
	ds_bpermute_b32 v151, v227, v162
	v_pk_mul_f32 v[154:155], v[92:93], v[154:155]
	v_pk_mul_f32 v[148:149], v[90:91], v[152:153]
	v_pk_mul_f32 v[156:157], v[88:89], v[156:157]
	v_cvt_pk_bf16_f32 v150, v148, v149
	s_waitcnt lgkmcnt(0)
	v_add_f32_e32 v148, v162, v151
	ds_bpermute_b32 v149, v226, v148
	v_pk_mul_f32 v[152:153], v[86:87], v[158:159]
	v_cvt_pk_bf16_f32 v151, v154, v155
	v_cvt_pk_bf16_f32 v152, v152, v153
	v_cvt_pk_bf16_f32 v153, v156, v157
	s_andn2_b64 vcc, exec, s[38:39]
	s_cbranch_vccnz .Lmy_wt_g2b_3
	global_store_dwordx4 v[160:161], v[150:153], off offset:256
.Lmy_wt_g2b_3r:
	s_and_saveexec_b64 s[68:69], s[36:37]
	v_readlane_b32 s58, v255, 24
	v_readlane_b32 s2, v252, 35
	v_readlane_b32 s59, v255, 25
	s_mov_b32 s96, s3
	s_cbranch_execz .LBB0_913
	v_lshlrev_b64 v[150:151], 6, v[214:215]
	v_lshl_add_u64 v[150:151], s[58:59], 0, v[150:151]
	v_lshl_add_u64 v[150:151], s[56:57], 2, v[150:151]
	s_lshl_b32 s48, s75, 2
	v_lshl_add_u64 v[150:151], v[150:151], 0, s[48:49]
	s_waitcnt lgkmcnt(0)
	v_add_f32_e32 v148, v148, v149
	global_store_dword v[150:151], v148, off
.LBB0_913:
	s_or_b64 exec, exec, s[68:69]
	v_readlane_b32 s4, v252, 3
	v_or_b32_e32 v218, 48, v214
	v_readlane_b32 s5, v252, 4
	v_readlane_b32 s7, v252, 6
	v_add_u32_e32 v148, 0xffffc030, v214
	v_ashrrev_i32_e32 v219, 31, v218
	v_cmp_gt_i32_e32 vcc, s21, v218
	v_readlane_b32 s6, v252, 5
	v_mov_b32_e32 v150, s7
	v_mov_b32_e32 v151, s5
	s_waitcnt lgkmcnt(0)
	v_cndmask_b32_e32 v149, 0, v219, vcc
	v_cndmask_b32_e32 v148, v148, v218, vcc
	v_cndmask_b32_e32 v151, v150, v151, vcc
	v_mov_b32_e32 v150, s6
	v_mov_b32_e32 v152, s4
	v_cndmask_b32_e32 v150, v150, v152, vcc
	v_lshlrev_b64 v[148:149], 12, v[148:149]
	v_lshl_add_u64 v[148:149], v[150:151], 0, v[148:149]
	v_lshl_add_u64 v[152:153], v[212:213], 2, v[148:149]
	global_load_dwordx4 v[156:159], v[152:153], off offset:16
	global_load_dwordx4 v[160:163], v[152:153], off
	global_load_dwordx4 v[148:151], v[152:153], off offset:528
	s_nop 0
	global_load_dwordx4 v[152:155], v[152:153], off offset:512
	v_pk_fma_f32 v[190:191], v[142:143], v[118:119], v[190:191]
	v_pk_fma_f32 v[188:189], v[140:141], v[116:117], v[188:189]
	v_pk_fma_f32 v[146:147], v[146:147], v[126:127], v[194:195]
	v_pk_fma_f32 v[144:145], v[144:145], v[124:125], v[192:193]
	v_pk_mul_f32 v[140:141], v[190:191], v[190:191]
	v_pk_mul_f32 v[142:143], v[188:189], v[188:189]
	v_pk_fma_f32 v[140:141], v[146:147], v[146:147], v[140:141]
	v_pk_fma_f32 v[142:143], v[144:145], v[144:145], v[142:143]
	v_lshlrev_b64 v[192:193], 11, v[220:221]
	v_add_f32_e32 v142, v142, v143
	v_add_f32_e32 v140, v140, v141
	v_lshl_add_u64 v[194:195], s[82:83], 0, v[192:193]
	v_add_f32_e32 v200, v142, v140
	v_cvt_pk_bf16_f32 v140, v144, v145
	v_cvt_pk_bf16_f32 v141, v146, v147
	v_cvt_pk_bf16_f32 v142, v188, v189
	v_cvt_pk_bf16_f32 v143, v190, v191
	v_lshl_add_u64 v[194:195], v[194:195], 0, v[210:211]
	s_andn2_b64 vcc, exec, s[38:39]
	s_cbranch_vccnz .Lmy_wt_g2b_4
	global_store_dwordx4 v[194:195], v[140:143], off
.Lmy_wt_g2b_4r:
	v_pk_fma_f32 v[138:139], v[138:139], v[106:107], v[186:187]
	v_pk_fma_f32 v[136:137], v[136:137], v[104:105], v[184:185]
	v_pk_mul_f32 v[142:143], v[114:115], v[146:147]
	v_pk_mul_f32 v[140:141], v[112:113], v[144:145]
	v_pk_mul_f32 v[144:145], v[110:111], v[190:191]
	v_pk_mul_f32 v[146:147], v[108:109], v[188:189]
	v_cvt_pk_bf16_f32 v140, v140, v141
	v_cvt_pk_bf16_f32 v141, v142, v143
	v_cvt_pk_bf16_f32 v143, v144, v145
	v_lshl_add_u64 v[144:145], s[22:23], 0, v[192:193]
	v_cvt_pk_bf16_f32 v142, v146, v147
	v_lshl_add_u64 v[144:145], v[144:145], 0, v[210:211]
	s_andn2_b64 vcc, exec, s[38:39]
	s_cbranch_vccnz .Lmy_wt_g2b_5
	global_store_dwordx4 v[144:145], v[140:143], off
.Lmy_wt_g2b_5r:
	v_readlane_b32 s8, v252, 7
	v_readlane_b32 s9, v252, 8
	v_pk_fma_f32 v[140:141], v[134:135], v[102:103], v[182:183]
	v_pk_fma_f32 v[142:143], v[132:133], v[100:101], v[180:181]
	v_pk_mul_f32 v[132:133], v[140:141], v[140:141]
	v_pk_mul_f32 v[134:135], v[142:143], v[142:143]
	v_pk_fma_f32 v[132:133], v[138:139], v[138:139], v[132:133]
	v_pk_fma_f32 v[134:135], v[136:137], v[136:137], v[134:135]
	v_add_f32_e32 v132, v132, v133
	v_add_f32_e32 v134, v134, v135
	v_add_f32_e32 v132, v134, v132
	v_add_f32_e32 v146, v200, v132
	v_cvt_pk_bf16_f32 v132, v136, v137
	v_cvt_pk_bf16_f32 v133, v138, v139
	v_cvt_pk_bf16_f32 v134, v142, v143
	v_cvt_pk_bf16_f32 v135, v140, v141
	s_andn2_b64 vcc, exec, s[38:39]
	s_cbranch_vccnz .Lmy_wt_g2b_6
	global_store_dwordx4 v[194:195], v[132:135], off offset:256
.Lmy_wt_g2b_6r:
	ds_bpermute_b32 v135, v227, v146
	v_pk_mul_f32 v[138:139], v[92:93], v[138:139]
	v_pk_mul_f32 v[132:133], v[90:91], v[136:137]
	v_pk_mul_f32 v[140:141], v[88:89], v[140:141]
	v_cvt_pk_bf16_f32 v134, v132, v133
	s_waitcnt lgkmcnt(0)
	v_add_f32_e32 v132, v146, v135
	ds_bpermute_b32 v133, v226, v132
	v_pk_mul_f32 v[136:137], v[86:87], v[142:143]
	v_cvt_pk_bf16_f32 v135, v138, v139
	v_cvt_pk_bf16_f32 v136, v136, v137
	v_cvt_pk_bf16_f32 v137, v140, v141
	v_readlane_b32 s10, v252, 9
	v_readlane_b32 s11, v252, 10
	v_readlane_b32 s12, v252, 11
	v_readlane_b32 s13, v252, 12
	v_readlane_b32 s14, v252, 13
	v_readlane_b32 s15, v252, 14
	v_readlane_b32 s16, v252, 15
	v_readlane_b32 s17, v252, 16
	v_readlane_b32 s18, v252, 17
	v_readlane_b32 s19, v252, 18
	s_andn2_b64 vcc, exec, s[38:39]
	s_cbranch_vccnz .Lmy_wt_g2b_7
	global_store_dwordx4 v[144:145], v[134:137], off offset:256
.Lmy_wt_g2b_7r:
	s_and_saveexec_b64 s[68:69], s[36:37]
	s_cbranch_execz .LBB0_915
	v_lshlrev_b64 v[134:135], 6, v[220:221]
	v_lshl_add_u64 v[134:135], s[58:59], 0, v[134:135]
	v_lshl_add_u64 v[134:135], s[56:57], 2, v[134:135]
	s_lshl_b32 s48, s75, 2
	v_lshl_add_u64 v[134:135], v[134:135], 0, s[48:49]
	s_waitcnt lgkmcnt(0)
	v_add_f32_e32 v132, v132, v133
	global_store_dword v[134:135], v132, off
.LBB0_915:
	s_or_b64 exec, exec, s[68:69]
	s_movk_i32 s4, 0x3f80
	v_cmp_gt_i32_e32 vcc, s4, v214
	v_readlane_b32 s4, v252, 3
	v_add_u32_e32 v180, 0x80, v214
	v_readlane_b32 s5, v252, 4
	v_readlane_b32 s7, v252, 6
	v_ashrrev_i32_e32 v181, 31, v180
	v_add_u32_e32 v132, 0xffffc080, v214
	v_readlane_b32 s6, v252, 5
	v_mov_b32_e32 v134, s7
	v_mov_b32_e32 v135, s5
	s_waitcnt lgkmcnt(0)
	v_cndmask_b32_e32 v133, 0, v181, vcc
	v_cndmask_b32_e32 v132, v132, v180, vcc
	v_cndmask_b32_e32 v135, v134, v135, vcc
	v_mov_b32_e32 v134, s6
	v_mov_b32_e32 v136, s4
	v_cndmask_b32_e32 v134, v134, v136, vcc
	v_lshlrev_b64 v[132:133], 12, v[132:133]
	v_lshl_add_u64 v[132:133], v[134:135], 0, v[132:133]
	v_lshl_add_u64 v[136:137], v[212:213], 2, v[132:133]
	global_load_dwordx4 v[140:143], v[136:137], off offset:16
	global_load_dwordx4 v[144:147], v[136:137], off
	global_load_dwordx4 v[132:135], v[136:137], off offset:528
	s_nop 0
	global_load_dwordx4 v[136:139], v[136:137], off offset:512
	v_pk_fma_f32 v[174:175], v[122:123], v[118:119], v[174:175]
	v_pk_fma_f32 v[172:173], v[120:121], v[116:117], v[172:173]
	v_pk_fma_f32 v[130:131], v[130:131], v[126:127], v[178:179]
	v_pk_fma_f32 v[128:129], v[128:129], v[124:125], v[176:177]
	v_pk_mul_f32 v[120:121], v[174:175], v[174:175]
	v_pk_mul_f32 v[122:123], v[172:173], v[172:173]
	v_pk_fma_f32 v[120:121], v[130:131], v[130:131], v[120:121]
	v_pk_fma_f32 v[122:123], v[128:129], v[128:129], v[122:123]
	v_lshlrev_b64 v[176:177], 11, v[216:217]
	v_add_f32_e32 v122, v122, v123
	v_add_f32_e32 v120, v120, v121
	v_lshl_add_u64 v[178:179], s[82:83], 0, v[176:177]
	v_add_f32_e32 v182, v122, v120
	v_cvt_pk_bf16_f32 v120, v128, v129
	v_cvt_pk_bf16_f32 v121, v130, v131
	v_cvt_pk_bf16_f32 v122, v172, v173
	v_cvt_pk_bf16_f32 v123, v174, v175
	v_lshl_add_u64 v[178:179], v[178:179], 0, v[210:211]
	s_andn2_b64 vcc, exec, s[38:39]
	s_cbranch_vccnz .Lmy_wt_g2b_8
	global_store_dwordx4 v[178:179], v[120:123], off
.Lmy_wt_g2b_8r:
	v_pk_fma_f32 v[96:97], v[96:97], v[106:107], v[170:171]
	v_pk_fma_f32 v[94:95], v[94:95], v[104:105], v[168:169]
	v_pk_mul_f32 v[122:123], v[114:115], v[130:131]
	v_pk_mul_f32 v[120:121], v[112:113], v[128:129]
	v_pk_mul_f32 v[128:129], v[110:111], v[174:175]
	v_pk_mul_f32 v[130:131], v[108:109], v[172:173]
	v_cvt_pk_bf16_f32 v120, v120, v121
	v_cvt_pk_bf16_f32 v121, v122, v123
	v_cvt_pk_bf16_f32 v123, v128, v129
	v_lshl_add_u64 v[128:129], s[22:23], 0, v[176:177]
	v_cvt_pk_bf16_f32 v122, v130, v131
	v_lshl_add_u64 v[128:129], v[128:129], 0, v[210:211]
	s_andn2_b64 vcc, exec, s[38:39]
	s_cbranch_vccnz .Lmy_wt_g2b_9
	global_store_dwordx4 v[128:129], v[120:123], off
.Lmy_wt_g2b_9r:
	v_readlane_b32 s8, v252, 7
	v_readlane_b32 s9, v252, 8
	v_pk_fma_f32 v[120:121], v[84:85], v[102:103], v[166:167]
	v_pk_fma_f32 v[122:123], v[82:83], v[100:101], v[164:165]
	v_pk_mul_f32 v[82:83], v[120:121], v[120:121]
	v_pk_mul_f32 v[84:85], v[122:123], v[122:123]
	v_pk_fma_f32 v[82:83], v[96:97], v[96:97], v[82:83]
	v_pk_fma_f32 v[84:85], v[94:95], v[94:95], v[84:85]
	v_add_f32_e32 v82, v82, v83
	v_add_f32_e32 v84, v84, v85
	v_add_f32_e32 v82, v84, v82
	v_add_f32_e32 v130, v182, v82
	ds_bpermute_b32 v131, v227, v130
	v_cvt_pk_bf16_f32 v82, v94, v95
	v_cvt_pk_bf16_f32 v83, v96, v97
	v_cvt_pk_bf16_f32 v84, v122, v123
	v_cvt_pk_bf16_f32 v85, v120, v121
	s_andn2_b64 vcc, exec, s[38:39]
	s_cbranch_vccnz .Lmy_wt_g2b_10
	global_store_dwordx4 v[178:179], v[82:85], off offset:256
.Lmy_wt_g2b_10r:
	v_pk_mul_f32 v[120:121], v[88:89], v[120:121]
	v_readlane_b32 s10, v252, 9
	v_pk_mul_f32 v[82:83], v[90:91], v[94:95]
	v_pk_mul_f32 v[84:85], v[92:93], v[96:97]
	v_cvt_pk_bf16_f32 v94, v82, v83
	s_waitcnt lgkmcnt(0)
	v_add_f32_e32 v82, v130, v131
	ds_bpermute_b32 v83, v226, v82
	v_pk_mul_f32 v[96:97], v[86:87], v[122:123]
	v_cvt_pk_bf16_f32 v95, v84, v85
	v_cvt_pk_bf16_f32 v96, v96, v97
	v_cvt_pk_bf16_f32 v97, v120, v121
	v_readlane_b32 s11, v252, 10
	v_readlane_b32 s12, v252, 11
	v_readlane_b32 s13, v252, 12
	v_readlane_b32 s14, v252, 13
	v_readlane_b32 s15, v252, 14
	v_readlane_b32 s16, v252, 15
	v_readlane_b32 s17, v252, 16
	v_readlane_b32 s18, v252, 17
	v_readlane_b32 s19, v252, 18
	s_andn2_b64 vcc, exec, s[38:39]
	s_cbranch_vccnz .Lmy_wt_g2b_11
	global_store_dwordx4 v[128:129], v[94:97], off offset:256
.Lmy_wt_g2b_11r:
	s_mov_b64 s[68:69], exec
	v_readlane_b32 s66, v252, 38
	v_readlane_b32 s62, v255, 27
	v_readlane_b32 s64, v255, 29
	v_readlane_b32 s70, v255, 37
	s_and_b64 s[4:5], s[68:69], s[36:37]
	v_readlane_b32 s67, v252, 39
	v_readlane_b32 s60, v255, 26
	v_readlane_b32 s63, v255, 28
	v_readlane_b32 s65, v255, 30
	v_readlane_b32 s61, v255, 35
	v_readlane_b32 s71, v255, 38
	s_movk_i32 s97, 0xff
	v_mov_b32_e32 v248, v228
	v_mov_b32_e32 v228, v231
	s_mov_b64 exec, s[4:5]
	s_cbranch_execz .LBB0_917
	v_lshlrev_b64 v[84:85], 6, v[216:217]
	v_lshl_add_u64 v[84:85], s[58:59], 0, v[84:85]
	v_lshl_add_u64 v[84:85], s[56:57], 2, v[84:85]
	s_lshl_b32 s48, s75, 2
	v_lshl_add_u64 v[84:85], v[84:85], 0, s[48:49]
	s_waitcnt lgkmcnt(0)
	v_add_f32_e32 v82, v82, v83
	global_store_dword v[84:85], v82, off
.LBB0_917:
	s_or_b64 exec, exec, s[68:69]
	s_movk_i32 s4, 0x3f70
	v_cmp_gt_i32_e32 vcc, s4, v214
	v_readlane_b32 s4, v252, 3
	v_add_u32_e32 v82, 0x90, v214
	v_add_u32_e32 v84, 0xffffc090, v214
	v_readlane_b32 s5, v252, 4
	v_readlane_b32 s7, v252, 6
	s_waitcnt lgkmcnt(0)
	v_ashrrev_i32_e32 v83, 31, v82
	v_cndmask_b32_e32 v82, v84, v82, vcc
	v_readlane_b32 s6, v252, 5
	v_mov_b32_e32 v84, s7
	v_mov_b32_e32 v85, s5
	v_cndmask_b32_e32 v83, 0, v83, vcc
	v_cndmask_b32_e32 v85, v84, v85, vcc
	v_mov_b32_e32 v84, s6
	v_mov_b32_e32 v94, s4
	v_cndmask_b32_e32 v84, v84, v94, vcc
	v_lshlrev_b64 v[82:83], 12, v[82:83]
	v_lshl_add_u64 v[82:83], v[84:85], 0, v[82:83]
	v_lshl_add_u64 v[94:95], v[212:213], 2, v[82:83]
	global_load_dwordx4 v[120:123], v[94:95], off offset:16
	global_load_dwordx4 v[128:131], v[94:95], off
	global_load_dwordx4 v[82:85], v[94:95], off offset:528
	s_nop 0
	global_load_dwordx4 v[94:97], v[94:95], off offset:512
	s_waitcnt vmcnt(19)
	v_pk_fma_f32 v[158:159], v[76:77], v[118:119], v[158:159]
	v_pk_fma_f32 v[156:157], v[74:75], v[116:117], v[156:157]
	s_waitcnt vmcnt(18)
	v_pk_fma_f32 v[80:81], v[80:81], v[126:127], v[162:163]
	v_pk_fma_f32 v[78:79], v[78:79], v[124:125], v[160:161]
	v_pk_mul_f32 v[74:75], v[158:159], v[158:159]
	v_pk_mul_f32 v[76:77], v[156:157], v[156:157]
	v_pk_fma_f32 v[74:75], v[80:81], v[80:81], v[74:75]
	v_pk_fma_f32 v[76:77], v[78:79], v[78:79], v[76:77]
	v_lshlrev_b64 v[160:161], 11, v[218:219]
	v_add_f32_e32 v76, v76, v77
	v_add_f32_e32 v74, v74, v75
	v_lshl_add_u64 v[162:163], s[82:83], 0, v[160:161]
	v_add_f32_e32 v164, v76, v74
	v_cvt_pk_bf16_f32 v74, v78, v79
	v_cvt_pk_bf16_f32 v75, v80, v81
	v_cvt_pk_bf16_f32 v76, v156, v157
	v_cvt_pk_bf16_f32 v77, v158, v159
	v_lshl_add_u64 v[162:163], v[162:163], 0, v[210:211]
	s_andn2_b64 vcc, exec, s[38:39]
	s_cbranch_vccnz .Lmy_wt_g2b_12
	global_store_dwordx4 v[162:163], v[74:77], off
.Lmy_wt_g2b_12r:
	s_waitcnt vmcnt(17)
	v_pk_fma_f32 v[72:73], v[72:73], v[106:107], v[154:155]
	v_pk_fma_f32 v[70:71], v[70:71], v[104:105], v[152:153]
	v_pk_mul_f32 v[76:77], v[114:115], v[80:81]
	v_pk_mul_f32 v[74:75], v[112:113], v[78:79]
	v_pk_mul_f32 v[78:79], v[110:111], v[158:159]
	v_pk_mul_f32 v[80:81], v[108:109], v[156:157]
	v_cvt_pk_bf16_f32 v74, v74, v75
	v_cvt_pk_bf16_f32 v75, v76, v77
	v_cvt_pk_bf16_f32 v77, v78, v79
	v_lshl_add_u64 v[78:79], s[22:23], 0, v[160:161]
	v_cvt_pk_bf16_f32 v76, v80, v81
	v_lshl_add_u64 v[78:79], v[78:79], 0, v[210:211]
	s_andn2_b64 vcc, exec, s[38:39]
	s_cbranch_vccnz .Lmy_wt_g2b_13
	global_store_dwordx4 v[78:79], v[74:77], off
.Lmy_wt_g2b_13r:
	v_readlane_b32 s8, v252, 7
	v_readlane_b32 s9, v252, 8
	v_pk_fma_f32 v[74:75], v[68:69], v[102:103], v[150:151]
	v_pk_fma_f32 v[76:77], v[66:67], v[100:101], v[148:149]
	v_pk_mul_f32 v[66:67], v[74:75], v[74:75]
	v_pk_mul_f32 v[68:69], v[76:77], v[76:77]
	v_pk_fma_f32 v[66:67], v[72:73], v[72:73], v[66:67]
	v_pk_fma_f32 v[68:69], v[70:71], v[70:71], v[68:69]
	v_add_f32_e32 v66, v66, v67
	v_add_f32_e32 v68, v68, v69
	v_add_f32_e32 v66, v68, v66
	v_add_f32_e32 v80, v164, v66
	v_cvt_pk_bf16_f32 v66, v70, v71
	v_cvt_pk_bf16_f32 v67, v72, v73
	v_cvt_pk_bf16_f32 v68, v76, v77
	v_cvt_pk_bf16_f32 v69, v74, v75
	s_andn2_b64 vcc, exec, s[38:39]
	s_cbranch_vccnz .Lmy_wt_g2b_14
	global_store_dwordx4 v[162:163], v[66:69], off offset:256
.Lmy_wt_g2b_14r:
	ds_bpermute_b32 v69, v227, v80
	v_pk_mul_f32 v[72:73], v[92:93], v[72:73]
	v_pk_mul_f32 v[66:67], v[90:91], v[70:71]
	v_pk_mul_f32 v[74:75], v[88:89], v[74:75]
	v_cvt_pk_bf16_f32 v68, v66, v67
	s_waitcnt lgkmcnt(0)
	v_add_f32_e32 v66, v80, v69
	ds_bpermute_b32 v67, v226, v66
	v_pk_mul_f32 v[70:71], v[86:87], v[76:77]
	v_cvt_pk_bf16_f32 v69, v72, v73
	v_cvt_pk_bf16_f32 v70, v70, v71
	v_cvt_pk_bf16_f32 v71, v74, v75
	v_readlane_b32 s10, v252, 9
	v_readlane_b32 s11, v252, 10
	v_readlane_b32 s12, v252, 11
	v_readlane_b32 s13, v252, 12
	v_readlane_b32 s14, v252, 13
	v_readlane_b32 s15, v252, 14
	v_readlane_b32 s16, v252, 15
	v_readlane_b32 s17, v252, 16
	v_readlane_b32 s18, v252, 17
	v_readlane_b32 s19, v252, 18
	s_andn2_b64 vcc, exec, s[38:39]
	s_cbranch_vccnz .Lmy_wt_g2b_15
	global_store_dwordx4 v[78:79], v[68:71], off offset:256
.Lmy_wt_g2b_15r:
	s_and_saveexec_b64 s[68:69], s[36:37]
	s_cbranch_execz .LBB0_919
	v_lshlrev_b64 v[68:69], 6, v[218:219]
	v_lshl_add_u64 v[68:69], s[58:59], 0, v[68:69]
	v_lshl_add_u64 v[68:69], s[56:57], 2, v[68:69]
	s_lshl_b32 s48, s75, 2
	v_lshl_add_u64 v[68:69], v[68:69], 0, s[48:49]
	s_waitcnt lgkmcnt(0)
	v_add_f32_e32 v66, v66, v67
	global_store_dword v[68:69], v66, off
.LBB0_919:
	s_or_b64 exec, exec, s[68:69]
	v_readlane_b32 s4, v252, 3
	v_or_b32_e32 v148, 32, v180
	v_readlane_b32 s5, v252, 4
	v_readlane_b32 s7, v252, 6
	v_ashrrev_i32_e32 v149, 31, v148
	v_add_u32_e32 v66, 0xffffc0a0, v214
	v_cmp_gt_i32_e32 vcc, s21, v148
	v_readlane_b32 s6, v252, 5
	v_mov_b32_e32 v68, s7
	v_mov_b32_e32 v69, s5
	s_waitcnt lgkmcnt(0)
	v_cndmask_b32_e32 v67, 0, v149, vcc
	v_cndmask_b32_e32 v66, v66, v148, vcc
	v_cndmask_b32_e32 v69, v68, v69, vcc
	v_mov_b32_e32 v68, s6
	v_mov_b32_e32 v70, s4
	v_cndmask_b32_e32 v68, v68, v70, vcc
	v_lshlrev_b64 v[66:67], 12, v[66:67]
	v_lshl_add_u64 v[66:67], v[68:69], 0, v[66:67]
	v_lshl_add_u64 v[70:71], v[212:213], 2, v[66:67]
	global_load_dwordx4 v[74:77], v[70:71], off offset:16
	global_load_dwordx4 v[78:81], v[70:71], off
	global_load_dwordx4 v[66:69], v[70:71], off offset:528
	s_nop 0
	global_load_dwordx4 v[70:73], v[70:71], off offset:512
	s_waitcnt vmcnt(19)
	v_pk_fma_f32 v[142:143], v[60:61], v[118:119], v[142:143]
	v_pk_fma_f32 v[140:141], v[58:59], v[116:117], v[140:141]
	s_waitcnt vmcnt(18)
	v_pk_fma_f32 v[64:65], v[64:65], v[126:127], v[146:147]
	v_pk_fma_f32 v[62:63], v[62:63], v[124:125], v[144:145]
	v_pk_mul_f32 v[58:59], v[142:143], v[142:143]
	v_pk_mul_f32 v[60:61], v[140:141], v[140:141]
	v_pk_fma_f32 v[58:59], v[64:65], v[64:65], v[58:59]
	v_pk_fma_f32 v[60:61], v[62:63], v[62:63], v[60:61]
	v_lshlrev_b64 v[144:145], 11, v[180:181]
	v_add_f32_e32 v60, v60, v61
	v_add_f32_e32 v58, v58, v59
	v_lshl_add_u64 v[146:147], s[82:83], 0, v[144:145]
	v_add_f32_e32 v150, v60, v58
	v_cvt_pk_bf16_f32 v58, v62, v63
	v_cvt_pk_bf16_f32 v59, v64, v65
	v_cvt_pk_bf16_f32 v60, v140, v141
	v_cvt_pk_bf16_f32 v61, v142, v143
	v_lshl_add_u64 v[146:147], v[146:147], 0, v[210:211]
	s_andn2_b64 vcc, exec, s[38:39]
	s_cbranch_vccnz .Lmy_wt_g2b_16
	global_store_dwordx4 v[146:147], v[58:61], off
.Lmy_wt_g2b_16r:
	s_waitcnt vmcnt(17)
	v_pk_fma_f32 v[56:57], v[56:57], v[106:107], v[138:139]
	v_pk_fma_f32 v[54:55], v[54:55], v[104:105], v[136:137]
	v_pk_mul_f32 v[60:61], v[114:115], v[64:65]
	v_pk_mul_f32 v[58:59], v[112:113], v[62:63]
	v_pk_mul_f32 v[62:63], v[110:111], v[142:143]
	v_pk_mul_f32 v[64:65], v[108:109], v[140:141]
	v_cvt_pk_bf16_f32 v58, v58, v59
	v_cvt_pk_bf16_f32 v59, v60, v61
	v_cvt_pk_bf16_f32 v61, v62, v63
	v_lshl_add_u64 v[62:63], s[22:23], 0, v[144:145]
	v_cvt_pk_bf16_f32 v60, v64, v65
	v_lshl_add_u64 v[62:63], v[62:63], 0, v[210:211]
	s_andn2_b64 vcc, exec, s[38:39]
	s_cbranch_vccnz .Lmy_wt_g2b_17
	global_store_dwordx4 v[62:63], v[58:61], off
.Lmy_wt_g2b_17r:
	v_readlane_b32 s8, v252, 7
	v_readlane_b32 s9, v252, 8
	v_pk_fma_f32 v[58:59], v[52:53], v[102:103], v[134:135]
	v_pk_fma_f32 v[60:61], v[50:51], v[100:101], v[132:133]
	v_pk_mul_f32 v[50:51], v[58:59], v[58:59]
	v_pk_mul_f32 v[52:53], v[60:61], v[60:61]
	v_pk_fma_f32 v[50:51], v[56:57], v[56:57], v[50:51]
	v_pk_fma_f32 v[52:53], v[54:55], v[54:55], v[52:53]
	v_add_f32_e32 v50, v50, v51
	v_add_f32_e32 v52, v52, v53
	v_add_f32_e32 v50, v52, v50
	v_add_f32_e32 v64, v150, v50
	v_cvt_pk_bf16_f32 v50, v54, v55
	v_cvt_pk_bf16_f32 v51, v56, v57
	v_cvt_pk_bf16_f32 v52, v60, v61
	v_cvt_pk_bf16_f32 v53, v58, v59
	s_andn2_b64 vcc, exec, s[38:39]
	s_cbranch_vccnz .Lmy_wt_g2b_18
	global_store_dwordx4 v[146:147], v[50:53], off offset:256
.Lmy_wt_g2b_18r:
	ds_bpermute_b32 v53, v227, v64
	v_pk_mul_f32 v[56:57], v[92:93], v[56:57]
	v_pk_mul_f32 v[50:51], v[90:91], v[54:55]
	v_pk_mul_f32 v[58:59], v[88:89], v[58:59]
	v_cvt_pk_bf16_f32 v52, v50, v51
	s_waitcnt lgkmcnt(0)
	v_add_f32_e32 v50, v64, v53
	ds_bpermute_b32 v51, v226, v50
	v_pk_mul_f32 v[54:55], v[86:87], v[60:61]
	v_cvt_pk_bf16_f32 v53, v56, v57
	v_cvt_pk_bf16_f32 v54, v54, v55
	v_cvt_pk_bf16_f32 v55, v58, v59
	v_readlane_b32 s10, v252, 9
	v_readlane_b32 s11, v252, 10
	v_readlane_b32 s12, v252, 11
	v_readlane_b32 s13, v252, 12
	v_readlane_b32 s14, v252, 13
	v_readlane_b32 s15, v252, 14
	v_readlane_b32 s16, v252, 15
	v_readlane_b32 s17, v252, 16
	v_readlane_b32 s18, v252, 17
	v_readlane_b32 s19, v252, 18
	s_andn2_b64 vcc, exec, s[38:39]
	s_cbranch_vccnz .Lmy_wt_g2b_19
	global_store_dwordx4 v[62:63], v[52:55], off offset:256
.Lmy_wt_g2b_19r:
	s_and_saveexec_b64 s[68:69], s[36:37]
	s_cbranch_execz .LBB0_921
	v_lshlrev_b64 v[52:53], 6, v[180:181]
	v_lshl_add_u64 v[52:53], s[58:59], 0, v[52:53]
	v_lshl_add_u64 v[52:53], s[56:57], 2, v[52:53]
	s_lshl_b32 s48, s75, 2
	v_lshl_add_u64 v[52:53], v[52:53], 0, s[48:49]
	s_waitcnt lgkmcnt(0)
	v_add_f32_e32 v50, v50, v51
	global_store_dword v[52:53], v50, off
.LBB0_921:
	s_or_b64 exec, exec, s[68:69]
	v_readlane_b32 s4, v252, 3
	v_or_b32_e32 v132, 48, v180
	v_readlane_b32 s5, v252, 4
	v_readlane_b32 s7, v252, 6
	v_ashrrev_i32_e32 v133, 31, v132
	v_add_u32_e32 v50, 0xffffc0b0, v214
	v_cmp_gt_i32_e32 vcc, s21, v132
	v_readlane_b32 s6, v252, 5
	v_mov_b32_e32 v52, s7
	v_mov_b32_e32 v53, s5
	s_waitcnt lgkmcnt(0)
	v_cndmask_b32_e32 v51, 0, v133, vcc
	v_cndmask_b32_e32 v50, v50, v132, vcc
	v_cndmask_b32_e32 v53, v52, v53, vcc
	v_mov_b32_e32 v52, s6
	v_mov_b32_e32 v54, s4
	v_cndmask_b32_e32 v52, v52, v54, vcc
	v_lshlrev_b64 v[50:51], 12, v[50:51]
	v_lshl_add_u64 v[50:51], v[52:53], 0, v[50:51]
	v_lshl_add_u64 v[54:55], v[212:213], 2, v[50:51]
	global_load_dwordx4 v[58:61], v[54:55], off offset:16
	global_load_dwordx4 v[62:65], v[54:55], off
	global_load_dwordx4 v[50:53], v[54:55], off offset:528
	s_nop 0
	global_load_dwordx4 v[54:57], v[54:55], off offset:512
	v_or_b32_e32 v134, 16, v180
	s_waitcnt vmcnt(19)
	v_pk_fma_f32 v[122:123], v[44:45], v[118:119], v[122:123]
	v_pk_fma_f32 v[120:121], v[42:43], v[116:117], v[120:121]
	v_ashrrev_i32_e32 v135, 31, v134
	s_waitcnt vmcnt(18)
	v_pk_fma_f32 v[48:49], v[48:49], v[126:127], v[130:131]
	v_pk_fma_f32 v[46:47], v[46:47], v[124:125], v[128:129]
	v_pk_mul_f32 v[42:43], v[122:123], v[122:123]
	v_pk_mul_f32 v[44:45], v[120:121], v[120:121]
	v_pk_fma_f32 v[42:43], v[48:49], v[48:49], v[42:43]
	v_pk_fma_f32 v[44:45], v[46:47], v[46:47], v[44:45]
	v_lshlrev_b64 v[128:129], 11, v[134:135]
	v_add_f32_e32 v44, v44, v45
	v_add_f32_e32 v42, v42, v43
	v_lshl_add_u64 v[130:131], s[82:83], 0, v[128:129]
	v_add_f32_e32 v136, v44, v42
	v_cvt_pk_bf16_f32 v42, v46, v47
	v_cvt_pk_bf16_f32 v43, v48, v49
	v_cvt_pk_bf16_f32 v44, v120, v121
	v_cvt_pk_bf16_f32 v45, v122, v123
	v_lshl_add_u64 v[130:131], v[130:131], 0, v[210:211]
	s_andn2_b64 vcc, exec, s[38:39]
	s_cbranch_vccnz .Lmy_wt_g2b_20
	global_store_dwordx4 v[130:131], v[42:45], off
.Lmy_wt_g2b_20r:
	s_waitcnt vmcnt(17)
	v_pk_fma_f32 v[40:41], v[40:41], v[106:107], v[96:97]
	v_pk_fma_f32 v[38:39], v[38:39], v[104:105], v[94:95]
	v_pk_mul_f32 v[44:45], v[114:115], v[48:49]
	v_pk_mul_f32 v[42:43], v[112:113], v[46:47]
	v_pk_mul_f32 v[46:47], v[110:111], v[122:123]
	v_pk_mul_f32 v[48:49], v[108:109], v[120:121]
	v_cvt_pk_bf16_f32 v42, v42, v43
	v_cvt_pk_bf16_f32 v43, v44, v45
	v_cvt_pk_bf16_f32 v45, v46, v47
	v_lshl_add_u64 v[46:47], s[22:23], 0, v[128:129]
	v_cvt_pk_bf16_f32 v44, v48, v49
	v_lshl_add_u64 v[46:47], v[46:47], 0, v[210:211]
	s_andn2_b64 vcc, exec, s[38:39]
	s_cbranch_vccnz .Lmy_wt_g2b_21
	global_store_dwordx4 v[46:47], v[42:45], off
.Lmy_wt_g2b_21r:
	v_readlane_b32 s8, v252, 7
	v_readlane_b32 s9, v252, 8
	v_pk_fma_f32 v[42:43], v[36:37], v[102:103], v[84:85]
	v_pk_fma_f32 v[44:45], v[34:35], v[100:101], v[82:83]
	v_pk_mul_f32 v[34:35], v[42:43], v[42:43]
	v_pk_mul_f32 v[36:37], v[44:45], v[44:45]
	v_pk_fma_f32 v[34:35], v[40:41], v[40:41], v[34:35]
	v_pk_fma_f32 v[36:37], v[38:39], v[38:39], v[36:37]
	v_add_f32_e32 v34, v34, v35
	v_add_f32_e32 v36, v36, v37
	v_add_f32_e32 v34, v36, v34
	v_add_f32_e32 v48, v136, v34
	v_cvt_pk_bf16_f32 v34, v38, v39
	v_cvt_pk_bf16_f32 v35, v40, v41
	v_cvt_pk_bf16_f32 v36, v44, v45
	v_cvt_pk_bf16_f32 v37, v42, v43
	s_andn2_b64 vcc, exec, s[38:39]
	s_cbranch_vccnz .Lmy_wt_g2b_22
	global_store_dwordx4 v[130:131], v[34:37], off offset:256
.Lmy_wt_g2b_22r:
	ds_bpermute_b32 v37, v227, v48
	v_pk_mul_f32 v[40:41], v[92:93], v[40:41]
	v_pk_mul_f32 v[34:35], v[90:91], v[38:39]
	v_pk_mul_f32 v[42:43], v[88:89], v[42:43]
	v_cvt_pk_bf16_f32 v36, v34, v35
	s_waitcnt lgkmcnt(0)
	v_add_f32_e32 v34, v48, v37
	ds_bpermute_b32 v35, v226, v34
	v_pk_mul_f32 v[38:39], v[86:87], v[44:45]
	v_cvt_pk_bf16_f32 v37, v40, v41
	v_cvt_pk_bf16_f32 v38, v38, v39
	v_cvt_pk_bf16_f32 v39, v42, v43
	v_readlane_b32 s10, v252, 9
	v_readlane_b32 s11, v252, 10
	v_readlane_b32 s12, v252, 11
	v_readlane_b32 s13, v252, 12
	v_readlane_b32 s14, v252, 13
	v_readlane_b32 s15, v252, 14
	v_readlane_b32 s16, v252, 15
	v_readlane_b32 s17, v252, 16
	v_readlane_b32 s18, v252, 17
	v_readlane_b32 s19, v252, 18
	s_andn2_b64 vcc, exec, s[38:39]
	s_cbranch_vccnz .Lmy_wt_g2b_23
	global_store_dwordx4 v[46:47], v[36:39], off offset:256

.LBB0_923:
	s_or_b64 exec, exec, s[68:69]
	s_waitcnt vmcnt(15) lgkmcnt(0)
	v_pk_fma_f32 v[34:35], v[28:29], v[118:119], v[76:77]
	v_pk_fma_f32 v[36:37], v[26:27], v[116:117], v[74:75]
	s_waitcnt vmcnt(14)
	v_pk_fma_f32 v[32:33], v[32:33], v[126:127], v[80:81]
	v_pk_fma_f32 v[30:31], v[30:31], v[124:125], v[78:79]
	v_pk_mul_f32 v[26:27], v[34:35], v[34:35]
	v_pk_mul_f32 v[28:29], v[36:37], v[36:37]
	v_pk_fma_f32 v[26:27], v[32:33], v[32:33], v[26:27]
	v_pk_fma_f32 v[28:29], v[30:31], v[30:31], v[28:29]
	v_lshlrev_b64 v[38:39], 11, v[148:149]
	v_add_f32_e32 v28, v28, v29
	v_add_f32_e32 v26, v26, v27
	v_lshl_add_u64 v[40:41], s[82:83], 0, v[38:39]
	v_add_f32_e32 v42, v28, v26
	v_cvt_pk_bf16_f32 v26, v30, v31
	v_cvt_pk_bf16_f32 v27, v32, v33
	v_cvt_pk_bf16_f32 v28, v36, v37
	v_cvt_pk_bf16_f32 v29, v34, v35
	v_lshl_add_u64 v[40:41], v[40:41], 0, v[210:211]
	s_andn2_b64 vcc, exec, s[38:39]
	s_cbranch_vccnz .Lmy_wt_g2b_24
	global_store_dwordx4 v[40:41], v[26:29], off
.Lmy_wt_g2b_24r:
	s_waitcnt vmcnt(13)
	v_pk_fma_f32 v[24:25], v[24:25], v[106:107], v[72:73]
	v_pk_fma_f32 v[22:23], v[22:23], v[104:105], v[70:71]
	v_pk_mul_f32 v[28:29], v[114:115], v[32:33]
	v_pk_mul_f32 v[26:27], v[112:113], v[30:31]
	v_pk_mul_f32 v[30:31], v[110:111], v[34:35]
	v_pk_mul_f32 v[32:33], v[108:109], v[36:37]
	v_cvt_pk_bf16_f32 v26, v26, v27
	v_cvt_pk_bf16_f32 v27, v28, v29
	v_cvt_pk_bf16_f32 v29, v30, v31
	v_lshl_add_u64 v[30:31], s[22:23], 0, v[38:39]
	v_cvt_pk_bf16_f32 v28, v32, v33
	v_lshl_add_u64 v[30:31], v[30:31], 0, v[210:211]
	s_andn2_b64 vcc, exec, s[38:39]
	s_cbranch_vccnz .Lmy_wt_g2b_25
	global_store_dwordx4 v[30:31], v[26:29], off
.Lmy_wt_g2b_25r:
	s_nop 1
	v_pk_fma_f32 v[26:27], v[20:21], v[102:103], v[68:69]
	v_pk_fma_f32 v[28:29], v[18:19], v[100:101], v[66:67]
	v_pk_mul_f32 v[18:19], v[26:27], v[26:27]
	v_pk_mul_f32 v[20:21], v[28:29], v[28:29]
	v_pk_fma_f32 v[18:19], v[24:25], v[24:25], v[18:19]
	v_pk_fma_f32 v[20:21], v[22:23], v[22:23], v[20:21]
	v_add_f32_e32 v18, v18, v19
	v_add_f32_e32 v20, v20, v21
	v_add_f32_e32 v18, v20, v18
	v_add_f32_e32 v32, v42, v18
	v_cvt_pk_bf16_f32 v18, v22, v23
	v_cvt_pk_bf16_f32 v19, v24, v25
	v_cvt_pk_bf16_f32 v20, v28, v29
	v_cvt_pk_bf16_f32 v21, v26, v27
	s_andn2_b64 vcc, exec, s[38:39]
	s_cbranch_vccnz .Lmy_wt_g2b_26
	global_store_dwordx4 v[40:41], v[18:21], off offset:256
.Lmy_wt_g2b_26r:
	ds_bpermute_b32 v21, v227, v32
	v_pk_mul_f32 v[24:25], v[92:93], v[24:25]
	v_pk_mul_f32 v[18:19], v[90:91], v[22:23]
	v_pk_mul_f32 v[26:27], v[88:89], v[26:27]
	v_cvt_pk_bf16_f32 v20, v18, v19
	s_waitcnt lgkmcnt(0)
	v_add_f32_e32 v18, v32, v21
	ds_bpermute_b32 v19, v226, v18
	v_pk_mul_f32 v[22:23], v[86:87], v[28:29]
	v_cvt_pk_bf16_f32 v21, v24, v25
	v_cvt_pk_bf16_f32 v22, v22, v23
	v_cvt_pk_bf16_f32 v23, v26, v27
	s_andn2_b64 vcc, exec, s[38:39]
	s_cbranch_vccnz .Lmy_wt_g2b_27
	global_store_dwordx4 v[30:31], v[20:23], off offset:256

.LBB0_925:
	s_or_b64 exec, exec, s[68:69]
	s_waitcnt vmcnt(11) lgkmcnt(0)
	v_pk_fma_f32 v[18:19], v[12:13], v[118:119], v[60:61]
	v_pk_fma_f32 v[20:21], v[10:11], v[116:117], v[58:59]
	s_waitcnt vmcnt(10)
	v_pk_fma_f32 v[16:17], v[16:17], v[126:127], v[64:65]
	v_pk_fma_f32 v[14:15], v[14:15], v[124:125], v[62:63]
	v_pk_mul_f32 v[10:11], v[18:19], v[18:19]
	v_pk_mul_f32 v[12:13], v[20:21], v[20:21]
	v_pk_fma_f32 v[10:11], v[16:17], v[16:17], v[10:11]
	v_pk_fma_f32 v[12:13], v[14:15], v[14:15], v[12:13]
	v_lshlrev_b64 v[22:23], 11, v[132:133]
	v_add_f32_e32 v12, v12, v13
	v_add_f32_e32 v10, v10, v11
	v_lshl_add_u64 v[24:25], s[82:83], 0, v[22:23]
	v_add_f32_e32 v26, v12, v10
	v_cvt_pk_bf16_f32 v10, v14, v15
	v_cvt_pk_bf16_f32 v11, v16, v17
	v_cvt_pk_bf16_f32 v12, v20, v21
	v_cvt_pk_bf16_f32 v13, v18, v19
	v_lshl_add_u64 v[24:25], v[24:25], 0, v[210:211]
	s_andn2_b64 vcc, exec, s[38:39]
	s_cbranch_vccnz .Lmy_wt_g2b_28
	global_store_dwordx4 v[24:25], v[10:13], off
.Lmy_wt_g2b_28r:
	s_waitcnt vmcnt(9)
	v_pk_fma_f32 v[8:9], v[8:9], v[106:107], v[56:57]
	v_pk_fma_f32 v[6:7], v[6:7], v[104:105], v[54:55]
	v_pk_mul_f32 v[12:13], v[114:115], v[16:17]
	v_pk_mul_f32 v[10:11], v[112:113], v[14:15]
	v_pk_mul_f32 v[14:15], v[110:111], v[18:19]
	v_pk_mul_f32 v[16:17], v[108:109], v[20:21]
	v_cvt_pk_bf16_f32 v10, v10, v11
	v_cvt_pk_bf16_f32 v11, v12, v13
	v_cvt_pk_bf16_f32 v13, v14, v15
	v_lshl_add_u64 v[14:15], s[22:23], 0, v[22:23]
	v_cvt_pk_bf16_f32 v12, v16, v17
	v_lshl_add_u64 v[14:15], v[14:15], 0, v[210:211]
	s_andn2_b64 vcc, exec, s[38:39]
	s_cbranch_vccnz .Lmy_wt_g2b_29
	global_store_dwordx4 v[14:15], v[10:13], off
.Lmy_wt_g2b_29r:
	s_nop 1
	v_pk_fma_f32 v[10:11], v[4:5], v[102:103], v[52:53]
	v_pk_fma_f32 v[12:13], v[2:3], v[100:101], v[50:51]
	v_pk_mul_f32 v[2:3], v[10:11], v[10:11]
	v_pk_mul_f32 v[4:5], v[12:13], v[12:13]
	v_pk_fma_f32 v[2:3], v[8:9], v[8:9], v[2:3]
	v_pk_fma_f32 v[4:5], v[6:7], v[6:7], v[4:5]
	v_add_f32_e32 v2, v2, v3
	v_add_f32_e32 v4, v4, v5
	v_add_f32_e32 v2, v4, v2
	v_add_f32_e32 v16, v26, v2
	v_cvt_pk_bf16_f32 v2, v6, v7
	v_cvt_pk_bf16_f32 v3, v8, v9
	v_cvt_pk_bf16_f32 v4, v12, v13
	v_cvt_pk_bf16_f32 v5, v10, v11
	s_andn2_b64 vcc, exec, s[38:39]
	s_cbranch_vccnz .Lmy_wt_g2b_30
	global_store_dwordx4 v[24:25], v[2:5], off offset:256
.Lmy_wt_g2b_30r:
	ds_bpermute_b32 v5, v227, v16
	v_pk_mul_f32 v[8:9], v[92:93], v[8:9]
	v_pk_mul_f32 v[2:3], v[90:91], v[6:7]
	v_pk_mul_f32 v[10:11], v[88:89], v[10:11]
	v_cvt_pk_bf16_f32 v4, v2, v3
	s_waitcnt lgkmcnt(0)
	v_add_f32_e32 v2, v16, v5
	ds_bpermute_b32 v3, v226, v2
	v_pk_mul_f32 v[6:7], v[86:87], v[12:13]
	v_cvt_pk_bf16_f32 v5, v8, v9
	v_cvt_pk_bf16_f32 v6, v6, v7
	v_cvt_pk_bf16_f32 v7, v10, v11
	s_andn2_b64 vcc, exec, s[38:39]
	s_cbranch_vccnz .Lmy_wt_g2b_31
	global_store_dwordx4 v[14:15], v[4:7], off offset:256

.Lmy_wt_g2b_0:
	global_store_dwordx4 v[242:243], v[156:159], off sc1
	s_branch .Lmy_wt_g2b_0r

.Lmy_wt_g2b_2:
	global_store_dwordx4 v[242:243], v[148:151], off offset:256 sc1
	s_branch .Lmy_wt_g2b_2r
.Lmy_wt_g2b_3:
	global_store_dwordx4 v[160:161], v[150:153], off offset:256 sc1
	s_branch .Lmy_wt_g2b_3r
.Lmy_wt_g2b_4:
	global_store_dwordx4 v[194:195], v[140:143], off sc1
	s_branch .Lmy_wt_g2b_4r

.Lmy_wt_g2b_6:
	global_store_dwordx4 v[194:195], v[132:135], off offset:256 sc1
	s_branch .Lmy_wt_g2b_6r

.Lmy_wt_g2b_8:
	global_store_dwordx4 v[178:179], v[120:123], off sc1
	s_branch .Lmy_wt_g2b_8r
.Lmy_wt_g2b_9:
	global_store_dwordx4 v[128:129], v[120:123], off sc1
	s_branch .Lmy_wt_g2b_9r
.Lmy_wt_g2b_10:
	global_store_dwordx4 v[178:179], v[82:85], off offset:256 sc1
	s_branch .Lmy_wt_g2b_10r
.Lmy_wt_g2b_11:
	global_store_dwordx4 v[128:129], v[94:97], off offset:256 sc1
	s_branch .Lmy_wt_g2b_11r

.Lmy_wt_g2b_16:
	global_store_dwordx4 v[146:147], v[58:61], off sc1
	s_branch .Lmy_wt_g2b_16r

.Lmy_wt_g2b_18:
	global_store_dwordx4 v[146:147], v[50:53], off offset:256 sc1
	s_branch .Lmy_wt_g2b_18r
.Lmy_wt_g2b_19:
	global_store_dwordx4 v[62:63], v[52:55], off offset:256 sc1
	s_branch .Lmy_wt_g2b_19r
.Lmy_wt_g2b_20:
	global_store_dwordx4 v[130:131], v[42:45], off sc1
	s_branch .Lmy_wt_g2b_20r
